# P4: the 8 waves of a workgroup start their unit loop staggered (wave w sleeps w x s_sleep 48) so that per-unit latency bubbles of the waves no longer coincide
# baseline (speedup 1.0000x reference)
.LBB0_416:
	v_ashrrev_i32_e32 v8, 4, v0
	s_add_u32 s38, s30, 0x13000000
	v_lshlrev_b32_e32 v1, 1, v0
	v_and_b32_e32 v6, 3, v0
	s_addc_u32 s39, s31, 0
	v_lshlrev_b32_e32 v4, 2, v8
	v_and_or_b32 v176, v1, 24, v6
	v_lshlrev_b32_e32 v6, 3, v0
	s_add_u32 s56, s30, 0x18000000
	v_mov_b32_e32 v2, s20
	v_mov_b32_e32 v3, s21
	v_ashrrev_i32_e32 v5, 31, v4
	v_ashrrev_i32_e32 v7, 31, v6
	s_addc_u32 s57, s31, 0
	v_lshl_add_u64 v[180:181], v[4:5], 2, v[2:3]
	v_lshlrev_b64 v[2:3], 2, v[6:7]
	s_cmpk_lg_i32 s34, 0x100
	v_lshl_add_u64 v[182:183], s[18:19], 0, v[2:3]
	s_mov_b64 s[4:5], 0x1000
	s_cselect_b64 s[20:21], -1, 0
	s_and_b32 s59, s86, 31
	s_bfe_u32 s66, s3, 0x10006
	v_lshl_add_u64 v[184:185], v[182:183], 0, s[4:5]
	v_lshl_add_u64 v[188:189], v[6:7], 1, s[30:31]
	s_mov_b64 s[4:5], 0x1d000000
	v_and_b32_e32 v221, 15, v0
	s_lshr_b32 s58, s86, 5
	s_bitset1_b32 s59, 7
	s_lshr_b32 s67, s3, 7
	v_lshl_add_u64 v[190:191], v[188:189], 0, s[4:5]
	s_mul_i32 s4, s66, 0x744
	s_cmp_eq_u32 s67, 2
	v_lshl_add_u64 v[186:187], s[22:23], 0, v[2:3]
	v_lshl_add_u32 v0, v8, 5, s4
	v_lshlrev_b32_e32 v2, 2, v221
	s_cselect_b32 s68, 24, 32
	v_lshlrev_b32_e32 v170, 3, v8
	v_sub_u32_e32 v0, v0, v2
	s_lshl_b32 s4, s67, 6
	v_ashrrev_i32_e32 v171, 31, v170
	s_lshl_b32 s69, s71, 3
	v_subrev_u32_e32 v0, s4, v0
	v_lshl_or_b32 v222, s67, 4, v221
	v_lshlrev_b64 v[172:173], 1, v[170:171]
	v_mov_b32_e32 v1, 0
	v_add_u32_e32 v0, 0, v0
	s_add_u32 s70, s30, 0x18000080
	s_mul_i32 s58, s58, 5
	v_lshl_add_u64 v[174:175], s[24:25], 0, v[172:173]
	v_med3_u32 v171, v222, 8, 56
	v_mov_b32_e32 v177, v1
	v_lshl_add_u64 v[178:179], v[4:5], 1, s[26:27]
	s_mov_b32 s23, 0
	v_add_u32_e32 v223, 0x32c, v0
	s_addc_u32 s71, s31, 0
	s_lshl_b32 s72, s66, 6
	s_or_b32 s73, s69, 2
	s_mov_b64 s[40:41], 0x80
	s_mov_b64 s[42:43], 0xc0
	s_movk_i32 s74, 0x1000
	s_mov_b64 s[44:45], 0x10000
	v_mov_b32_e32 v224, 0x358637bd
	s_brev_b32 s75, 52
	s_mov_b32 s76, 0
	v_readlane_b32 s6, v254, 10
	s_nop 3
	s_cmp_eq_u32 s6, 0
	s_cbranch_scc1 .Lstg4_done
.Lstg4_loop:
	s_sleep 48
	s_sub_u32 s6, s6, 1
	s_cmp_lg_u32 s6, 0
	s_cbranch_scc1 .Lstg4_loop
.Lstg4_done:
	s_branch .LBB0_419
